# previous best plus: RG-LRU step loops issue the eight conv prefetch row loads unconditionally (rows are never negative inside the loop), dropping 64 compare/zero-fill/exec instructions per step and pa
# speedup vs baseline: 1.0008x; 1.0008x over previous
; #define LAS __attribute__((address_space(3)))
; template <bool PASSB>
; __device__ __forceinline__ void lru_unit(LAS unsigned char* lds, const Params& p, int b, int hd, int chunk) {
;     ...
;         for (int tb = 0; tb < 4; ++tb) {
;             f32x4 ar = (f32x4){0.f, 0.f, 0.f, 0.f}, ai = (f32x4){0.f, 0.f, 0.f, 0.f};
; #pragma unroll
;             for (int ks = 0; ks < 4; ++ks) {
;                 const bf16x8 a = *(const LAS bf16x8*)(XCB + (tb * 16 + fr) * 272 + (ks * 32 + fq * 8) * 2);
;                 ar = __builtin_amdgcn_mfma_f32_16x16x32_bf16(a, wf[0][ks], ar, 0, 0, 0);
;                 ai = __builtin_amdgcn_mfma_f32_16x16x32_bf16(a, wf[1][ks], ai, 0, 0, 0);
;             }
; #pragma unroll
;             for (int j = 0; j < 4; ++j) {
;                 const int token = fq * 16 + tb * 4 + j;
;                 const float xcv = XCF[token * 132 + chl];
;                 const float e1 = __expf(fminf(-(ar[j] + brv), 40.f)), e2 = __expf(fminf(-(ai[j] + biv), 40.f));
;                 const float inv = __builtin_amdgcn_rcpf((1.0f + e1) * (1.0f + e2));
;                 const float r = inv * (1.0f + e2), ig = inv * (1.0f + e1);
;                 const float a = __expf(clv * r);
;                 const float bb = __builtin_amdgcn_sqrtf(fmaxf(1.0f - a * a, 0.f)) * (ig * xcv);
;                 hrun = a * hrun + bb; prun *= a;
;                 if (PASSB) { hl[tb * 4 + j] = hrun; pl[tb * 4 + j] = prun; }
;             }
;         }
.LBB0_493:
	v_add3_u32 v132, s28, v110, v127
	ds_read_b128 v[134:137], v132
	ds_read_b128 v[138:141], v132 offset:64
	ds_read_b128 v[146:149], v132 offset:128
	v_lshl_add_u32 v131, v124, 2, s28
	v_lshlrev_b32_e32 v104, 2, v125
	s_waitcnt lgkmcnt(2)
	v_mfma_f32_16x16x32_bf16 v[142:145], v[134:137], v[24:27], 0
	v_add3_u32 v131, v131, v104, v126
	v_add_u32_e32 v133, 0x4400, v131
	ds_read2_b32 v[150:151], v133 offset1:132
	v_mfma_f32_16x16x32_bf16 v[134:137], v[134:137], v[28:31], 0
	s_add_i32 s0, s0, 64
	s_add_i32 s11, s11, 1
	s_cmpk_eq_i32 s0, 0x3c0
	s_waitcnt lgkmcnt(2)
	v_mfma_f32_16x16x32_bf16 v[142:145], v[138:141], v[16:19], v[142:145]
	v_mfma_f32_16x16x32_bf16 v[134:137], v[138:141], v[20:23], v[134:137]
	ds_read_b128 v[138:141], v132 offset:192
	s_waitcnt lgkmcnt(2)
	v_mfma_f32_16x16x32_bf16 v[142:145], v[146:149], v[8:11], v[142:145]
	v_mfma_f32_16x16x32_bf16 v[134:137], v[146:149], v[12:15], v[134:137]
	s_waitcnt lgkmcnt(0)
	v_mfma_f32_16x16x32_bf16 v[142:145], v[138:141], v[0:3], v[142:145]
	v_mfma_f32_16x16x32_bf16 v[134:137], v[138:141], v[4:7], v[134:137]
	s_nop 6
	v_fma_f32 v133, v142, s72, v200
	v_fma_f32 v134, v134, s72, v201
	v_min_f32_e32 v133, s73, v133
	v_min_f32_e32 v134, s73, v134
	v_fma_f32 v138, v143, s72, v200
	v_fma_f32 v135, v135, s72, v201
	v_exp_f32_e32 v133, v133
	v_exp_f32_e32 v134, v134
	v_min_f32_e32 v138, s73, v138
	v_min_f32_e32 v135, s73, v135
	v_exp_f32_e32 v138, v138
	v_exp_f32_e32 v135, v135
	v_add_f32_e32 v133, 1.0, v133
	v_add_f32_e32 v134, 1.0, v134
	v_mul_f32_e32 v139, v133, v134
	v_rcp_f32_e32 v139, v139
	v_add_f32_e32 v138, 1.0, v138
	v_add_f32_e32 v135, 1.0, v135
	v_mul_f32_e32 v140, v138, v135
	v_rcp_f32_e32 v140, v140
	v_mul_f32_e32 v134, v134, v139
	v_mul_f32_e32 v134, v202, v134
	v_mul_f32_e32 v135, v135, v140
	v_mul_f32_e32 v138, v138, v140
	v_fma_f32 v140, v144, s72, v200
	v_fma_f32 v136, v136, s72, v201
	v_exp_f32_e32 v134, v134
	v_min_f32_e32 v140, s73, v140
	v_min_f32_e32 v136, s73, v136
	v_exp_f32_e32 v140, v140
	v_exp_f32_e32 v136, v136
	v_mul_f32_e32 v133, v133, v139
	v_fma_f32 v139, -v134, v134, 1.0 clamp
	v_sqrt_f32_e32 v139, v139
	v_mul_f32_e32 v135, v202, v135
	v_add_f32_e32 v142, 1.0, v140
	v_add_f32_e32 v136, 1.0, v136
	v_mul_f32_e32 v140, v142, v136
	v_exp_f32_e32 v135, v135
	v_rcp_f32_e32 v143, v140
	v_mul_f32_e32 v133, v150, v133
	v_mul_f32_e32 v133, v133, v139
	v_fmac_f32_e32 v133, 0, v134
	v_fma_f32 v139, -v135, v135, 1.0 clamp
	v_mul_f32_e32 v133, v135, v133
	v_mul_f32_e32 v152, v134, v135
	v_mul_f32_e32 v135, v136, v143
	v_mul_f32_e32 v135, v202, v135
	v_sqrt_f32_e32 v139, v139
	v_exp_f32_e32 v153, v135
	v_mul_f32_e32 v138, v151, v138
	v_add_u32_e32 v134, 0x4800, v131
	v_fmac_f32_e32 v133, v138, v139
	ds_read2_b32 v[150:151], v134 offset0:8 offset1:140
	ds_read_b128 v[138:141], v132 offset:4352
	v_fma_f32 v134, -v153, v153, 1.0 clamp
	v_sqrt_f32_e32 v155, v134
	v_fma_f32 v134, v145, s72, v200
	v_min_f32_e32 v134, s73, v134
	v_mul_f32_e32 v154, v142, v143
	ds_read_b128 v[142:145], v132 offset:4416
	v_exp_f32_e32 v156, v134
	v_fma_f32 v134, v137, s72, v201
	v_min_f32_e32 v157, s73, v134
	s_waitcnt lgkmcnt(1)
	v_mfma_f32_16x16x32_bf16 v[146:149], v[138:141], v[24:27], 0
	v_mul_f32_e32 v150, v150, v154
	v_add_f32_e32 v154, 1.0, v156
	v_mul_f32_e32 v133, v153, v133
	v_mfma_f32_16x16x32_bf16 v[134:137], v[138:141], v[28:31], 0
	v_exp_f32_e32 v157, v157
	ds_read_b128 v[138:141], v132 offset:4480
	s_waitcnt lgkmcnt(1)
	v_mfma_f32_16x16x32_bf16 v[146:149], v[142:145], v[16:19], v[146:149]
	v_fmac_f32_e32 v133, v150, v155
	v_add_f32_e32 v156, 1.0, v157
	v_mfma_f32_16x16x32_bf16 v[134:137], v[142:145], v[20:23], v[134:137]
	v_mul_f32_e32 v142, v154, v156
	v_rcp_f32_e32 v157, v142
	ds_read_b128 v[142:145], v132 offset:4544
	s_waitcnt lgkmcnt(1)
	v_mfma_f32_16x16x32_bf16 v[146:149], v[138:141], v[8:11], v[146:149]
	v_mul_f32_e32 v150, v156, v157
	v_mfma_f32_16x16x32_bf16 v[134:137], v[138:141], v[12:15], v[134:137]
	v_mul_f32_e32 v138, v202, v150
	v_exp_f32_e32 v150, v138
	s_waitcnt lgkmcnt(0)
	v_mfma_f32_16x16x32_bf16 v[138:141], v[142:145], v[0:3], v[146:149]
	v_mul_f32_e32 v133, v150, v133
	v_mfma_f32_16x16x32_bf16 v[134:137], v[142:145], v[4:7], v[134:137]
	s_nop 0
	v_fma_f32 v148, -v150, v150, 1.0 clamp
	s_nop 3
	v_fma_f32 v138, v138, s72, v200
	v_min_f32_e32 v138, s73, v138
	v_exp_f32_e32 v138, v138
	v_fma_f32 v134, v134, s72, v201
	v_min_f32_e32 v134, s73, v134
	v_exp_f32_e32 v134, v134
	v_add_f32_e32 v138, 1.0, v138
	v_fma_f32 v139, v139, s72, v200
	v_fma_f32 v135, v135, s72, v201
	v_add_f32_e32 v134, 1.0, v134
	v_mul_f32_e32 v143, v138, v134
	v_rcp_f32_e32 v144, v143
	v_min_f32_e32 v139, s73, v139
	v_min_f32_e32 v135, s73, v135
	v_exp_f32_e32 v139, v139
	v_exp_f32_e32 v135, v135
	v_mul_f32_e32 v134, v134, v144
	v_mul_f32_e32 v134, v202, v134
	v_mul_f32_e32 v147, v154, v157
	v_sqrt_f32_e32 v142, v148
	v_add_f32_e32 v139, 1.0, v139
	v_add_f32_e32 v135, 1.0, v135
	v_mul_f32_e32 v143, v151, v147
	v_exp_f32_e32 v134, v134
	v_mul_f32_e32 v147, v139, v135
	v_rcp_f32_e32 v147, v147
	v_mul_f32_e32 v146, v153, v152
	v_fmac_f32_e32 v133, v143, v142
	v_add_u32_e32 v142, 0x4c00, v131
	v_mul_f32_e32 v145, v150, v146
	ds_read2_b32 v[142:143], v142 offset0:16 offset1:148
	v_fma_f32 v146, -v134, v134, 1.0 clamp
	v_mul_f32_e32 v135, v135, v147
	v_fma_f32 v140, v140, s72, v200
	v_fma_f32 v136, v136, s72, v201
	v_sqrt_f32_e32 v146, v146
	v_mul_f32_e32 v135, v202, v135
	v_min_f32_e32 v140, s73, v140
	v_min_f32_e32 v136, s73, v136
	v_mul_f32_e32 v138, v138, v144
	v_exp_f32_e32 v135, v135
	v_exp_f32_e32 v140, v140
	v_exp_f32_e32 v136, v136
	s_waitcnt lgkmcnt(0)
; #define LAS __attribute__((address_space(3)))
; template <bool PASSB>
; __device__ __forceinline__ void lru_unit(LAS unsigned char* lds, const Params& p, int b, int hd, int chunk) {
;     ...
;         for (int tb = 0; tb < 4; ++tb) {
;             f32x4 ar = (f32x4){0.f, 0.f, 0.f, 0.f}, ai = (f32x4){0.f, 0.f, 0.f, 0.f};
; #pragma unroll
;             for (int ks = 0; ks < 4; ++ks) {
;                 const bf16x8 a = *(const LAS bf16x8*)(XCB + (tb * 16 + fr) * 272 + (ks * 32 + fq * 8) * 2);
;                 ar = __builtin_amdgcn_mfma_f32_16x16x32_bf16(a, wf[0][ks], ar, 0, 0, 0);
;                 ai = __builtin_amdgcn_mfma_f32_16x16x32_bf16(a, wf[1][ks], ai, 0, 0, 0);
;             }
; #pragma unroll
;             for (int j = 0; j < 4; ++j) {
;                 const int token = fq * 16 + tb * 4 + j;
;                 const float xcv = XCF[token * 132 + chl];
;                 const float e1 = __expf(fminf(-(ar[j] + brv), 40.f)), e2 = __expf(fminf(-(ai[j] + biv), 40.f));
;                 const float inv = __builtin_amdgcn_rcpf((1.0f + e1) * (1.0f + e2));
;                 const float r = inv * (1.0f + e2), ig = inv * (1.0f + e1);
;                 const float a = __expf(clv * r);
;                 const float bb = __builtin_amdgcn_sqrtf(fmaxf(1.0f - a * a, 0.f)) * (ig * xcv);
;                 hrun = a * hrun + bb; prun *= a;
;                 if (PASSB) { hl[tb * 4 + j] = hrun; pl[tb * 4 + j] = prun; }
;             }
;         }
	v_mul_f32_e32 v138, v142, v138
	v_mul_f32_e32 v138, v138, v146
	v_fmac_f32_e32 v138, v133, v134
	v_mul_f32_e32 v152, v135, v138
	v_add_f32_e32 v138, 1.0, v140
	v_add_f32_e32 v136, 1.0, v136
	v_mul_f32_e32 v140, v138, v136
	v_rcp_f32_e32 v140, v140
	v_mul_f32_e32 v133, v145, v134
	v_mul_f32_e32 v134, v139, v147
	v_fma_f32 v139, -v135, v135, 1.0 clamp
	v_mul_f32_e32 v133, v135, v133
	v_mul_f32_e32 v135, v136, v140
	v_mul_f32_e32 v135, v202, v135
	v_sqrt_f32_e32 v139, v139
	v_exp_f32_e32 v153, v135
	v_mul_f32_e32 v134, v143, v134
	v_fmac_f32_e32 v152, v134, v139
	v_add_u32_e32 v134, 0x5000, v131
	ds_read2_b32 v[150:151], v134 offset0:24 offset1:156
	ds_read_b128 v[142:145], v132 offset:8704
	v_fma_f32 v134, -v153, v153, 1.0 clamp
	v_sqrt_f32_e32 v155, v134
	v_fma_f32 v134, v141, s72, v200
	v_min_f32_e32 v134, s73, v134
	v_mul_f32_e32 v154, v138, v140
	ds_read_b128 v[138:141], v132 offset:8768
	v_exp_f32_e32 v156, v134
	v_fma_f32 v134, v137, s72, v201
	v_min_f32_e32 v157, s73, v134
	s_waitcnt lgkmcnt(1)
	v_mfma_f32_16x16x32_bf16 v[146:149], v[142:145], v[24:27], 0
	v_mul_f32_e32 v150, v150, v154
	v_add_f32_e32 v154, 1.0, v156
	v_mul_f32_e32 v152, v153, v152
	v_mfma_f32_16x16x32_bf16 v[134:137], v[142:145], v[28:31], 0
	v_exp_f32_e32 v157, v157
	ds_read_b128 v[142:145], v132 offset:8832
	s_waitcnt lgkmcnt(1)
	v_mfma_f32_16x16x32_bf16 v[146:149], v[138:141], v[16:19], v[146:149]
	v_fmac_f32_e32 v152, v150, v155
	v_add_f32_e32 v156, 1.0, v157
	v_mul_f32_e32 v133, v153, v133
	v_mfma_f32_16x16x32_bf16 v[134:137], v[138:141], v[20:23], v[134:137]
	v_mul_f32_e32 v138, v154, v156
	v_rcp_f32_e32 v157, v138
	ds_read_b128 v[138:141], v132 offset:8896
	s_waitcnt lgkmcnt(1)
	v_mfma_f32_16x16x32_bf16 v[146:149], v[142:145], v[8:11], v[146:149]
	v_mul_f32_e32 v150, v156, v157
	v_mfma_f32_16x16x32_bf16 v[134:137], v[142:145], v[12:15], v[134:137]
	v_mul_f32_e32 v142, v202, v150
	v_exp_f32_e32 v150, v142
	s_waitcnt lgkmcnt(0)
	v_mfma_f32_16x16x32_bf16 v[142:145], v[138:141], v[0:3], v[146:149]
	v_mul_f32_e32 v133, v150, v133
	v_mfma_f32_16x16x32_bf16 v[134:137], v[138:141], v[4:7], v[134:137]
	s_nop 0
	v_fma_f32 v147, -v150, v150, 1.0 clamp
	s_nop 3
	v_fma_f32 v138, v142, s72, v200
	v_min_f32_e32 v138, s73, v138
	v_exp_f32_e32 v138, v138
	v_fma_f32 v134, v134, s72, v201
	v_min_f32_e32 v134, s73, v134
	v_exp_f32_e32 v134, v134
	v_add_f32_e32 v140, 1.0, v138
	v_fma_f32 v143, v143, s72, v200
	v_add_f32_e32 v134, 1.0, v134
	v_mul_f32_e32 v138, v140, v134
	v_rcp_f32_e32 v141, v138
	v_fma_f32 v135, v135, s72, v201
	v_sqrt_f32_e32 v139, v147
	v_min_f32_e32 v143, s73, v143
	v_mul_f32_e32 v134, v134, v141
	v_mul_f32_e32 v134, v202, v134
	v_min_f32_e32 v135, s73, v135
	v_exp_f32_e32 v134, v134
	v_mul_f32_e32 v146, v154, v157
	v_exp_f32_e32 v143, v143
	v_exp_f32_e32 v135, v135
	v_mul_f32_e32 v138, v151, v146
	v_mul_f32_e32 v142, v150, v152
	v_fmac_f32_e32 v142, v138, v139
	v_add_u32_e32 v138, 0x5400, v131
	ds_read2_b32 v[138:139], v138 offset0:32 offset1:164
	v_fma_f32 v146, -v134, v134, 1.0 clamp
	v_add_f32_e32 v143, 1.0, v143
	v_add_f32_e32 v135, 1.0, v135
	v_mul_f32_e32 v140, v140, v141
	v_fma_f32 v141, v144, s72, v200
	v_fma_f32 v136, v136, s72, v201
	v_sqrt_f32_e32 v146, v146
	v_mul_f32_e32 v147, v143, v135
	v_min_f32_e32 v141, s73, v141
	v_min_f32_e32 v136, s73, v136
	v_rcp_f32_e32 v147, v147
	v_exp_f32_e32 v141, v141
	v_exp_f32_e32 v136, v136
	s_waitcnt lgkmcnt(0)
	v_mul_f32_e32 v138, v138, v140
	v_mul_f32_e32 v138, v138, v146
	v_mul_f32_e32 v135, v135, v147
	v_fmac_f32_e32 v138, v142, v134
	v_mul_f32_e32 v133, v133, v134
	v_mul_f32_e32 v134, v143, v147
	v_mul_f32_e32 v135, v202, v135
	v_mul_f32_e32 v134, v139, v134
	v_add_f32_e32 v139, 1.0, v141
	v_add_f32_e32 v136, 1.0, v136
	v_mul_f32_e32 v141, v139, v136
	v_exp_f32_e32 v135, v135
	v_rcp_f32_e32 v141, v141
	v_mul_f32_e32 v153, v135, v133
	v_mul_f32_e32 v133, v136, v141
	v_fma_f32 v140, -v135, v135, 1.0 clamp
	v_mul_f32_e32 v133, v202, v133
	v_sqrt_f32_e32 v140, v140
	v_exp_f32_e32 v154, v133
	v_mul_f32_e32 v152, v135, v138
	v_add_u32_e32 v133, 0x5800, v131
	v_fmac_f32_e32 v152, v134, v140
	v_fma_f32 v134, -v154, v154, 1.0 clamp
	v_sqrt_f32_e32 v155, v134
	v_fma_f32 v134, v145, s72, v200
	ds_read2_b32 v[150:151], v133 offset0:40 offset1:172
	v_mul_f32_e32 v133, v139, v141
	ds_read_b128 v[138:141], v132 offset:13056
	v_min_f32_e32 v134, s73, v134
	v_exp_f32_e32 v146, v134
	v_fma_f32 v134, v137, s72, v201
	v_min_f32_e32 v147, s73, v134
	ds_read_b128 v[134:137], v132 offset:13120
	v_exp_f32_e32 v147, v147
	s_waitcnt lgkmcnt(1)
	v_mfma_f32_16x16x32_bf16 v[142:145], v[138:141], v[24:27], 0
	v_mul_f32_e32 v133, v150, v133
	v_add_f32_e32 v150, 1.0, v146
	v_add_f32_e32 v156, 1.0, v147
	v_mfma_f32_16x16x32_bf16 v[138:141], v[138:141], v[28:31], 0
	ds_read_b128 v[146:149], v132 offset:13184
	v_mul_f32_e32 v157, v150, v156
	v_rcp_f32_e32 v157, v157
	s_waitcnt lgkmcnt(1)
	v_mfma_f32_16x16x32_bf16 v[142:145], v[134:137], v[16:19], v[142:145]
	v_mul_f32_e32 v152, v154, v152
	v_fmac_f32_e32 v152, v133, v155
	v_mul_f32_e32 v133, v156, v157
	v_mfma_f32_16x16x32_bf16 v[134:137], v[134:137], v[20:23], v[138:141]
	s_nop 2
	ds_read_b128 v[138:141], v132 offset:13248
	v_mul_f32_e32 v132, v202, v133
	s_waitcnt lgkmcnt(1)
	v_mfma_f32_16x16x32_bf16 v[142:145], v[146:149], v[8:11], v[142:145]
	v_exp_f32_e32 v155, v132
	v_mfma_f32_16x16x32_bf16 v[132:135], v[146:149], v[12:15], v[134:137]
	v_fma_f32 v146, -v155, v155, 1.0 clamp
	v_sqrt_f32_e32 v146, v146
	s_waitcnt lgkmcnt(0)
; __device__ __forceinline__ unsigned cvt_pk_bf16(float lo, float hi) { unsigned r; asm volatile("v_cvt_pk_bf16_f32 %0, %1, %2" : "=v"(r) : "v"(lo), "v"(hi)); return r; }
; template <bool PASSB>
; __device__ __forceinline__ void lru_unit(LAS unsigned char* lds, const Params& p, int b, int hd, int chunk) {
;     ...
;             for (int j = 0; j < 4; ++j) {
;                 const int token = fq * 16 + tb * 4 + j;
;                 const float xcv = XCF[token * 132 + chl];
;                 const float e1 = __expf(fminf(-(ar[j] + brv), 40.f)), e2 = __expf(fminf(-(ai[j] + biv), 40.f));
;                 const float inv = __builtin_amdgcn_rcpf((1.0f + e1) * (1.0f + e2));
;                 const float r = inv * (1.0f + e2), ig = inv * (1.0f + e1);
;                 const float a = __expf(clv * r);
;                 const float bb = __builtin_amdgcn_sqrtf(fmaxf(1.0f - a * a, 0.f)) * (ig * xcv);
;                 hrun = a * hrun + bb; prun *= a;
;                 if (PASSB) { hl[tb * 4 + j] = hrun; pl[tb * 4 + j] = prun; }
;             }
;         }
;         const float P0 = __shfl(prun, fr), H0 = __shfl(hrun, fr), P1 = __shfl(prun, fr + 16), H1 = __shfl(hrun, fr + 16);
;         const float P2 = __shfl(prun, fr + 32), H2 = __shfl(hrun, fr + 32), P3 = __shfl(prun, fr + 48), H3 = __shfl(hrun, fr + 48);
;         const float s0 = P0 * Cst + H0, s1 = P1 * s0 + H1, s2 = P2 * s1 + H2, s3 = P3 * s2 + H3;
;         const float cin = fq == 0 ? Cst : (fq == 1 ? s0 : (fq == 2 ? s1 : s2));
;         Cst = s3;
;         if (PASSB) {
; #pragma unroll
;             for (int q = 0; q < 16; ++q) {
;                 const float hv = hl[q] + pl[q] * cin;
;                 const float gt = __uint_as_float(((unsigned)gvv[q]) << 16);
;                 YA[obase + (size_t)q * 1024] = (bf16_t)(cvt_pk_bf16(hv * gt, 0.f) & 0xffffu);
;             }
;         } else {
;             Pacc *= (P0 * P1) * (P2 * P3);
	v_mfma_f32_16x16x32_bf16 v[142:145], v[138:141], v[0:3], v[142:145]
	v_mul_f32_e32 v137, v150, v157
	v_mul_f32_e32 v137, v151, v137
	v_mul_f32_e32 v136, v154, v153
	v_mfma_f32_16x16x32_bf16 v[132:135], v[138:141], v[4:7], v[132:135]
	s_nop 3
	v_fma_f32 v138, v142, s72, v200
	s_nop 2
	v_fma_f32 v132, v132, s72, v201
	v_min_f32_e32 v138, s73, v138
	v_min_f32_e32 v132, s73, v132
	v_exp_f32_e32 v138, v138
	v_exp_f32_e32 v139, v132
	v_mul_f32_e32 v132, v155, v152
	v_fmac_f32_e32 v132, v137, v146
	v_add_f32_e32 v138, 1.0, v138
	v_add_f32_e32 v139, 1.0, v139
	v_mul_f32_e32 v137, v138, v139
	v_rcp_f32_e32 v140, v137
	v_fma_f32 v133, v133, s72, v201
	v_min_f32_e32 v133, s73, v133
	v_mul_f32_e32 v139, v139, v140
	v_mul_f32_e32 v140, v138, v140
	v_mul_f32_e32 v138, v202, v139
	v_fma_f32 v139, v143, s72, v200
	v_min_f32_e32 v139, s73, v139
	v_exp_f32_e32 v139, v139
	v_exp_f32_e32 v133, v133
	v_mul_f32_e32 v142, v155, v136
	v_add_u32_e32 v136, 0x5c00, v131
	v_add_f32_e32 v143, 1.0, v139
	v_add_f32_e32 v146, 1.0, v133
	ds_read2_b32 v[136:137], v136 offset0:48 offset1:180
	v_mul_f32_e32 v133, v143, v146
	v_rcp_f32_e32 v147, v133
	v_exp_f32_e32 v138, v138
	s_waitcnt lgkmcnt(0)
	v_mul_f32_e32 v133, v136, v140
	v_fma_f32 v134, v134, s72, v201
	v_mul_f32_e32 v140, v146, v147
	v_fma_f32 v141, -v138, v138, 1.0 clamp
	v_mul_f32_e32 v140, v202, v140
	v_sqrt_f32_e32 v139, v141
	v_exp_f32_e32 v141, v140
	v_mul_f32_e32 v136, v132, v138
	v_min_f32_e32 v134, s73, v134
	v_pk_fma_f32 v[132:133], v[132:133], v[138:139], v[136:137] op_sel_hi:[1,1,0]
	v_mul_f32_e32 v136, v142, v138
	v_fma_f32 v138, -v141, v141, 1.0 clamp
	v_sqrt_f32_e32 v140, v138
	v_fma_f32 v138, v144, s72, v200
	v_min_f32_e32 v138, s73, v138
	v_exp_f32_e32 v138, v138
	v_exp_f32_e32 v139, v134
	v_mul_f32_e32 v132, v143, v147
	v_mul_f32_e32 v132, v137, v132
	v_add_f32_e32 v142, 1.0, v138
	v_add_f32_e32 v137, 1.0, v139
	v_mul_f32_e32 v138, v142, v137
	v_rcp_f32_e32 v143, v138
	v_mul_f32_e32 v134, v132, v140
	v_pk_fma_f32 v[132:133], v[132:133], v[140:141], v[134:135] op_sel_hi:[1,1,0]
	v_add_u32_e32 v131, 0x6000, v131
	v_mul_f32_e32 v132, v137, v143
	v_mul_f32_e32 v132, v202, v132
	v_exp_f32_e32 v137, v132
	v_fma_f32 v132, v145, s72, v200
	v_min_f32_e32 v132, s73, v132
	v_exp_f32_e32 v134, v132
	v_fma_f32 v132, v135, s72, v201
	v_min_f32_e32 v132, s73, v132
	v_exp_f32_e32 v135, v132
	v_mul_f32_e32 v140, v141, v136
	ds_read2_b32 v[138:139], v131 offset0:56 offset1:188
	v_mul_f32_e32 v131, v142, v143
	v_pk_add_f32 v[134:135], v[134:135], 1.0 op_sel_hi:[1,0]
	v_fma_f32 v132, -v137, v137, 1.0 clamp
	v_mul_f32_e32 v136, v134, v135
	v_rcp_f32_e32 v142, v136
	v_sqrt_f32_e32 v136, v132
	s_waitcnt lgkmcnt(0)
	v_mul_f32_e32 v132, v138, v131
	v_mul_f32_e32 v131, v135, v142
	v_mul_f32_e32 v131, v202, v131
	v_exp_f32_e32 v141, v131
	v_mul_f32_e32 v138, v132, v136
	v_pk_fma_f32 v[132:133], v[132:133], v[136:137], v[138:139] op_sel_hi:[1,1,0]
	v_mul_f32_e32 v131, v137, v140
	v_fma_f32 v132, -v141, v141, 1.0 clamp
	v_sqrt_f32_e32 v140, v132
	v_mul_f32_e32 v132, v134, v142
	v_mul_f32_e32 v132, v139, v132
	v_mul_f32_e32 v134, v133, v141
	v_pk_fma_f32 v[132:133], v[132:133], v[140:141], v[134:135] op_sel_hi:[1,1,0]
	v_mul_f32_e32 v131, v141, v131
	ds_bpermute_b32 v134, v119, v131
	ds_bpermute_b32 v133, v119, v132
	ds_bpermute_b32 v136, v119, v131 offset:64
	ds_bpermute_b32 v138, v119, v132 offset:64
	ds_bpermute_b32 v135, v119, v131 offset:128
	ds_bpermute_b32 v139, v119, v132 offset:128
	ds_bpermute_b32 v132, v119, v132 offset:192
	ds_bpermute_b32 v137, v119, v131 offset:192
	s_waitcnt lgkmcnt(6)
	v_fmac_f32_e32 v133, v113, v134
	s_waitcnt lgkmcnt(4)
	v_fmac_f32_e32 v138, v133, v136
	s_waitcnt lgkmcnt(2)
	v_fmac_f32_e32 v139, v138, v135
	s_waitcnt lgkmcnt(1)
	v_mov_b32_e32 v113, v132
	s_waitcnt lgkmcnt(0)
	v_pk_mul_f32 v[132:133], v[134:135], v[136:137]
	v_fmac_f32_e32 v113, v139, v137
	v_mul_f32_e32 v131, v132, v133
	v_mul_f32_e32 v108, v108, v131
	s_cbranch_scc1 .LBB0_510
; #define LAS __attribute__((address_space(3)))
; __device__ __forceinline__ unsigned cvt_pk_bf16(float lo, float hi) { unsigned r; asm volatile("v_cvt_pk_bf16_f32 %0, %1, %2" : "=v"(r) : "v"(lo), "v"(hi)); return r; }
; __device__ __forceinline__ float bflo(unsigned w) { return __uint_as_float(w << 16); }
; __device__ __forceinline__ float bfhi(unsigned w) { return __uint_as_float(w & 0xffff0000u); }
; #define LRU_LOADX(st_) do { const int t0_ = chunk * LRU_LC + (st_) * 64; _Pragma("unroll") for (int i_ = 0; i_ < 2; ++i_) _Pragma("unroll") for (int k_ = 0; k_ < 4; ++k_) { \
;         const int ts_ = t0_ + tok + 32 * i_ - 3 + k_; xw[i_][k_] = (ts_ >= 0) ? *(const u32x4*)(xbase + (size_t)ts_ * 1024) : (u32x4){0u, 0u, 0u, 0u}; } } while (0)
; template <bool PASSB>
; __device__ __forceinline__ void lru_unit(LAS unsigned char* lds, const Params& p, int b, int hd, int chunk) {
;     ...
; #pragma unroll
;         for (int i = 0; i < 2; ++i) {
;             const int token = tok + 32 * i;
;             f32x4 a0 = cb0, a1 = cb1;
; #pragma unroll
;             for (int k = 0; k < 4; ++k) {
;                 const u32x4 x4 = xw[i][k];
;                 a0[0] += cw0[k][0] * bflo(x4.x); a0[1] += cw0[k][1] * bfhi(x4.x); a0[2] += cw0[k][2] * bflo(x4.y); a0[3] += cw0[k][3] * bfhi(x4.y);
;                 a1[0] += cw1[k][0] * bflo(x4.z); a1[1] += cw1[k][1] * bfhi(x4.z); a1[2] += cw1[k][2] * bflo(x4.w); a1[3] += cw1[k][3] * bfhi(x4.w);
;             }
;             u32x4 w; w.x = cvt_pk_bf16(a0[0], a0[1]); w.y = cvt_pk_bf16(a0[2], a0[3]); w.z = cvt_pk_bf16(a1[0], a1[1]); w.w = cvt_pk_bf16(a1[2], a1[3]);
;             *(LAS u32x4*)(XCB + (((token >> 2) & 3) * 16 + (token >> 4) * 4 + (token & 3)) * 272 + ch8 * 2) = w;
;             *(LAS f32x4*)(XCF + token * 132 + ch8) = a0; *(LAS f32x4*)(XCF + token * 132 + ch8 + 4) = a1;
;         }
;         __syncthreads();
;         if (st + 1 < NST) LRU_LOADX(st + 1);
.LBB0_494:
	s_waitcnt vmcnt(0)
	v_lshlrev_b32_e32 v132, 16, v76
	v_and_b32_e32 v133, 0xffff0000, v76
	v_lshlrev_b32_e32 v76, 16, v77
	v_and_b32_e32 v77, 0xffff0000, v77
	v_pk_fma_f32 v[132:133], v[52:53], v[132:133], v[68:69]
	v_lshlrev_b32_e32 v134, 16, v84
	v_and_b32_e32 v135, 0xffff0000, v84
	v_pk_fma_f32 v[76:77], v[54:55], v[76:77], v[70:71]
	v_lshlrev_b32_e32 v84, 16, v85
	v_and_b32_e32 v85, 0xffff0000, v85
	v_pk_fma_f32 v[132:133], v[64:65], v[134:135], v[132:133]
	v_lshlrev_b32_e32 v134, 16, v80
	v_and_b32_e32 v135, 0xffff0000, v80
	v_pk_fma_f32 v[76:77], v[66:67], v[84:85], v[76:77]
	v_lshlrev_b32_e32 v80, 16, v81
	v_and_b32_e32 v81, 0xffff0000, v81
	v_pk_fma_f32 v[132:133], v[56:57], v[134:135], v[132:133]
	v_lshlrev_b32_e32 v134, 16, v96
	v_and_b32_e32 v135, 0xffff0000, v96
	v_pk_fma_f32 v[76:77], v[58:59], v[80:81], v[76:77]
	v_lshlrev_b32_e32 v80, 16, v97
	v_and_b32_e32 v81, 0xffff0000, v97
	v_pk_fma_f32 v[132:133], v[60:61], v[134:135], v[132:133]
	v_pk_fma_f32 v[134:135], v[62:63], v[80:81], v[76:77]
	v_lshlrev_b32_e32 v76, 16, v78
	v_and_b32_e32 v77, 0xffff0000, v78
	v_pk_fma_f32 v[76:77], v[32:33], v[76:77], v[48:49]
	v_lshlrev_b32_e32 v80, 16, v86
	v_and_b32_e32 v81, 0xffff0000, v86
	s_bitcmp1_b32 s11, 0
	v_pk_fma_f32 v[76:77], v[44:45], v[80:81], v[76:77]
	v_lshlrev_b32_e32 v80, 16, v82
	v_and_b32_e32 v81, 0xffff0000, v82
	s_cselect_b32 s12, 0xc800, 0
	v_pk_fma_f32 v[76:77], v[36:37], v[80:81], v[76:77]
	v_lshlrev_b32_e32 v80, 16, v98
	v_and_b32_e32 v81, 0xffff0000, v98
	v_lshlrev_b32_e32 v78, 16, v79
	v_and_b32_e32 v79, 0xffff0000, v79
	s_add_i32 s28, s12, 0
	v_pk_fma_f32 v[76:77], v[40:41], v[80:81], v[76:77]
	v_pk_fma_f32 v[78:79], v[34:35], v[78:79], v[50:51]
	v_lshlrev_b32_e32 v80, 16, v87
	v_and_b32_e32 v81, 0xffff0000, v87
	v_add_u32_e32 v104, s28, v114
	v_pk_fma_f32 v[78:79], v[46:47], v[80:81], v[78:79]
	v_lshlrev_b32_e32 v80, 16, v83
	v_and_b32_e32 v81, 0xffff0000, v83
	v_pk_fma_f32 v[78:79], v[38:39], v[80:81], v[78:79]
	v_lshlrev_b32_e32 v80, 16, v99
	v_and_b32_e32 v81, 0xffff0000, v99
	v_add_u32_e32 v84, v104, v130
	v_pk_fma_f32 v[78:79], v[42:43], v[80:81], v[78:79]
	v_cvt_pk_bf16_f32 v80, v132, v133
	v_cvt_pk_bf16_f32 v81, v134, v135
	v_cvt_pk_bf16_f32 v82, v76, v77
	v_add_u32_e32 v131, s0, v118
	v_cvt_pk_bf16_f32 v83, v78, v79
	ds_write_b128 v84, v[80:83]
	v_add3_u32 v84, s28, v112, v129
	ds_write_b128 v84, v[132:135] offset:17408
	ds_write_b128 v84, v[76:79] offset:17424
	v_lshlrev_b32_e32 v76, 16, v72
	v_and_b32_e32 v77, 0xffff0000, v72
	v_pk_fma_f32 v[76:77], v[52:53], v[76:77], v[68:69]
	v_lshlrev_b32_e32 v78, 16, v92
	v_and_b32_e32 v79, 0xffff0000, v92
	v_pk_fma_f32 v[76:77], v[64:65], v[78:79], v[76:77]
	v_lshlrev_b32_e32 v78, 16, v88
	v_and_b32_e32 v79, 0xffff0000, v88
	v_pk_fma_f32 v[76:77], v[56:57], v[78:79], v[76:77]
	v_lshlrev_b32_e32 v78, 16, v100
	v_and_b32_e32 v79, 0xffff0000, v100
	v_lshlrev_b32_e32 v72, 16, v73
	v_and_b32_e32 v73, 0xffff0000, v73
	v_pk_fma_f32 v[76:77], v[60:61], v[78:79], v[76:77]
	v_pk_fma_f32 v[72:73], v[54:55], v[72:73], v[70:71]
	v_lshlrev_b32_e32 v78, 16, v93
	v_and_b32_e32 v79, 0xffff0000, v93
	v_pk_fma_f32 v[72:73], v[66:67], v[78:79], v[72:73]
	v_lshlrev_b32_e32 v78, 16, v89
	v_and_b32_e32 v79, 0xffff0000, v89
	v_pk_fma_f32 v[72:73], v[58:59], v[78:79], v[72:73]
	v_lshlrev_b32_e32 v78, 16, v101
	v_and_b32_e32 v79, 0xffff0000, v101
	v_pk_fma_f32 v[78:79], v[62:63], v[78:79], v[72:73]
	v_lshlrev_b32_e32 v72, 16, v74
	v_and_b32_e32 v73, 0xffff0000, v74
	v_pk_fma_f32 v[72:73], v[32:33], v[72:73], v[48:49]
	v_lshlrev_b32_e32 v80, 16, v94
	v_and_b32_e32 v81, 0xffff0000, v94
	v_pk_fma_f32 v[72:73], v[44:45], v[80:81], v[72:73]
	v_lshlrev_b32_e32 v80, 16, v90
	v_and_b32_e32 v81, 0xffff0000, v90
	v_pk_fma_f32 v[72:73], v[36:37], v[80:81], v[72:73]
	v_lshlrev_b32_e32 v80, 16, v102
	v_and_b32_e32 v81, 0xffff0000, v102
	v_lshlrev_b32_e32 v74, 16, v75
	v_and_b32_e32 v75, 0xffff0000, v75
	v_pk_fma_f32 v[72:73], v[40:41], v[80:81], v[72:73]
	v_pk_fma_f32 v[74:75], v[34:35], v[74:75], v[50:51]
	v_lshlrev_b32_e32 v80, 16, v95
	v_and_b32_e32 v81, 0xffff0000, v95
	v_pk_fma_f32 v[74:75], v[46:47], v[80:81], v[74:75]
	v_lshlrev_b32_e32 v80, 16, v91
	v_and_b32_e32 v81, 0xffff0000, v91
	v_pk_fma_f32 v[74:75], v[38:39], v[80:81], v[74:75]
	v_lshlrev_b32_e32 v80, 16, v103
	v_and_b32_e32 v81, 0xffff0000, v103
	v_pk_fma_f32 v[74:75], v[42:43], v[80:81], v[74:75]
	v_cvt_pk_bf16_f32 v80, v76, v77
	v_cvt_pk_bf16_f32 v81, v78, v79
	v_cvt_pk_bf16_f32 v82, v72, v73
	v_add_u32_e32 v85, v104, v128
	v_cvt_pk_bf16_f32 v83, v74, v75
	v_add_u32_e32 v104, 61, v131
	ds_write_b128 v85, v[80:83]
	ds_write_b128 v84, v[76:79] offset:34304
	ds_write_b128 v84, v[72:75] offset:34320
	s_waitcnt lgkmcnt(0)
	s_barrier
	v_lshlrev_b64 v[72:73], 11, v[104:105]
	v_lshl_add_u64 v[72:73], v[116:117], 0, v[72:73]
	global_load_dwordx4 v[76:79], v[72:73], off
.LBB0_496:
	v_add_u32_e32 v72, 62, v131
	v_mov_b32_e32 v73, v105
	v_lshlrev_b64 v[72:73], 11, v[72:73]
	v_lshl_add_u64 v[72:73], v[116:117], 0, v[72:73]
	global_load_dwordx4 v[84:87], v[72:73], off
.LBB0_498:
	v_add_u32_e32 v72, 63, v131
	v_mov_b32_e32 v73, v105
	v_lshlrev_b64 v[72:73], 11, v[72:73]
	v_lshl_add_u64 v[72:73], v[116:117], 0, v[72:73]
	global_load_dwordx4 v[80:83], v[72:73], off
.LBB0_500:
	v_add_u32_e32 v74, 64, v131
	v_mov_b32_e32 v75, v105
	v_lshlrev_b64 v[74:75], 11, v[74:75]
	v_lshl_add_u64 v[74:75], v[116:117], 0, v[74:75]
	global_load_dwordx4 v[96:99], v[74:75], off
.LBB0_502:
	v_add_u32_e32 v72, 0x5d, v131
	v_mov_b32_e32 v73, v105
	v_lshlrev_b64 v[72:73], 11, v[72:73]
	v_lshl_add_u64 v[72:73], v[116:117], 0, v[72:73]
	global_load_dwordx4 v[72:75], v[72:73], off
.LBB0_504:
	v_add_u32_e32 v90, 0x5e, v131
	v_mov_b32_e32 v91, v105
	v_lshlrev_b64 v[90:91], 11, v[90:91]
	v_lshl_add_u64 v[90:91], v[116:117], 0, v[90:91]
	global_load_dwordx4 v[92:95], v[90:91], off
.LBB0_506:
	v_add_u32_e32 v88, 0x5f, v131
	v_mov_b32_e32 v89, v105
	v_lshlrev_b64 v[88:89], 11, v[88:89]
	v_lshl_add_u64 v[88:89], v[116:117], 0, v[88:89]
	global_load_dwordx4 v[88:91], v[88:89], off
.LBB0_508:
	v_add_u32_e32 v104, 0x60, v131
	v_lshlrev_b64 v[100:101], 11, v[104:105]
	v_lshl_add_u64 v[100:101], v[116:117], 0, v[100:101]
	global_load_dwordx4 v[100:103], v[100:101], off
	s_branch .LBB0_493

; #define LAS __attribute__((address_space(3)))
; __device__ __forceinline__ unsigned cvt_pk_bf16(float lo, float hi) { unsigned r; asm volatile("v_cvt_pk_bf16_f32 %0, %1, %2" : "=v"(r) : "v"(lo), "v"(hi)); return r; }
; __device__ __forceinline__ float bflo(unsigned w) { return __uint_as_float(w << 16); }
; __device__ __forceinline__ float bfhi(unsigned w) { return __uint_as_float(w & 0xffff0000u); }
; #define LRU_LOADX(st_) do { const int t0_ = chunk * LRU_LC + (st_) * 64; _Pragma("unroll") for (int i_ = 0; i_ < 2; ++i_) _Pragma("unroll") for (int k_ = 0; k_ < 4; ++k_) { \
;         const int ts_ = t0_ + tok + 32 * i_ - 3 + k_; xw[i_][k_] = (ts_ >= 0) ? *(const u32x4*)(xbase + (size_t)ts_ * 1024) : (u32x4){0u, 0u, 0u, 0u}; } } while (0)
; template <bool PASSB>
; __device__ __forceinline__ void lru_unit(LAS unsigned char* lds, const Params& p, int b, int hd, int chunk) {
;     ...
; #pragma unroll
;         for (int i = 0; i < 2; ++i) {
;             const int token = tok + 32 * i;
;             f32x4 a0 = cb0, a1 = cb1;
; #pragma unroll
;             for (int k = 0; k < 4; ++k) {
;                 const u32x4 x4 = xw[i][k];
;                 a0[0] += cw0[k][0] * bflo(x4.x); a0[1] += cw0[k][1] * bfhi(x4.x); a0[2] += cw0[k][2] * bflo(x4.y); a0[3] += cw0[k][3] * bfhi(x4.y);
;                 a1[0] += cw1[k][0] * bflo(x4.z); a1[1] += cw1[k][1] * bfhi(x4.z); a1[2] += cw1[k][2] * bflo(x4.w); a1[3] += cw1[k][3] * bfhi(x4.w);
;             }
;             u32x4 w; w.x = cvt_pk_bf16(a0[0], a0[1]); w.y = cvt_pk_bf16(a0[2], a0[3]); w.z = cvt_pk_bf16(a1[0], a1[1]); w.w = cvt_pk_bf16(a1[2], a1[3]);
;             *(LAS u32x4*)(XCB + (((token >> 2) & 3) * 16 + (token >> 4) * 4 + (token & 3)) * 272 + ch8 * 2) = w;
;             *(LAS f32x4*)(XCF + token * 132 + ch8) = a0; *(LAS f32x4*)(XCF + token * 132 + ch8 + 4) = a1;
;         }
;         __syncthreads();
;         if (st + 1 < NST) LRU_LOADX(st + 1);
.LBB0_599:
	s_waitcnt vmcnt(16)
	v_lshlrev_b32_e32 v104, 16, v72
	v_and_b32_e32 v105, 0xffff0000, v72
	v_lshlrev_b32_e32 v72, 16, v73
	v_and_b32_e32 v73, 0xffff0000, v73
	v_pk_fma_f32 v[104:105], v[52:53], v[104:105], v[68:69]
	v_lshlrev_b32_e32 v106, 16, v80
	v_and_b32_e32 v107, 0xffff0000, v80
	v_pk_fma_f32 v[72:73], v[54:55], v[72:73], v[70:71]
	v_lshlrev_b32_e32 v80, 16, v81
	v_and_b32_e32 v81, 0xffff0000, v81
	v_pk_fma_f32 v[104:105], v[56:57], v[106:107], v[104:105]
	v_lshlrev_b32_e32 v106, 16, v84
	v_and_b32_e32 v107, 0xffff0000, v84
	v_pk_fma_f32 v[72:73], v[58:59], v[80:81], v[72:73]
	v_lshlrev_b32_e32 v80, 16, v85
	v_and_b32_e32 v81, 0xffff0000, v85
	v_pk_fma_f32 v[104:105], v[60:61], v[106:107], v[104:105]
	v_lshlrev_b32_e32 v106, 16, v96
	v_and_b32_e32 v107, 0xffff0000, v96
	v_pk_fma_f32 v[72:73], v[62:63], v[80:81], v[72:73]
	v_lshlrev_b32_e32 v80, 16, v97
	v_and_b32_e32 v81, 0xffff0000, v97
	v_pk_fma_f32 v[104:105], v[64:65], v[106:107], v[104:105]
	v_pk_fma_f32 v[106:107], v[66:67], v[80:81], v[72:73]
	v_lshlrev_b32_e32 v72, 16, v74
	v_and_b32_e32 v73, 0xffff0000, v74
	v_pk_fma_f32 v[72:73], v[32:33], v[72:73], v[48:49]
	v_lshlrev_b32_e32 v80, 16, v82
	v_and_b32_e32 v81, 0xffff0000, v82
	s_bitcmp1_b32 s14, 0
	v_pk_fma_f32 v[72:73], v[36:37], v[80:81], v[72:73]
	v_lshlrev_b32_e32 v80, 16, v86
	v_and_b32_e32 v81, 0xffff0000, v86
	s_cselect_b32 s10, 0xc800, 0
	v_pk_fma_f32 v[72:73], v[40:41], v[80:81], v[72:73]
	v_lshlrev_b32_e32 v80, 16, v98
	v_and_b32_e32 v81, 0xffff0000, v98
	v_lshlrev_b32_e32 v74, 16, v75
	v_and_b32_e32 v75, 0xffff0000, v75
	s_add_i32 s12, s10, 0
	v_pk_fma_f32 v[72:73], v[44:45], v[80:81], v[72:73]
	v_pk_fma_f32 v[74:75], v[34:35], v[74:75], v[50:51]
	v_lshlrev_b32_e32 v80, 16, v83
	v_and_b32_e32 v81, 0xffff0000, v83
	v_add_u32_e32 v108, s12, v120
	v_pk_fma_f32 v[74:75], v[38:39], v[80:81], v[74:75]
	v_lshlrev_b32_e32 v80, 16, v87
	v_and_b32_e32 v81, 0xffff0000, v87
	v_pk_fma_f32 v[74:75], v[42:43], v[80:81], v[74:75]
	v_lshlrev_b32_e32 v80, 16, v99
	v_and_b32_e32 v81, 0xffff0000, v99
	v_add_u32_e32 v84, v108, v139
	v_pk_fma_f32 v[74:75], v[46:47], v[80:81], v[74:75]
	v_cvt_pk_bf16_f32 v80, v104, v105
	v_cvt_pk_bf16_f32 v81, v106, v107
	v_cvt_pk_bf16_f32 v82, v72, v73
	v_add_u32_e32 v85, v108, v131
	v_cvt_pk_bf16_f32 v83, v74, v75
	ds_write_b128 v84, v[80:83]
	v_add3_u32 v84, s12, v118, v138
	ds_write_b128 v84, v[104:107] offset:17408
	ds_write_b128 v84, v[72:75] offset:17424
	v_lshlrev_b32_e32 v72, 16, v76
	v_and_b32_e32 v73, 0xffff0000, v76
	v_pk_fma_f32 v[72:73], v[52:53], v[72:73], v[68:69]
	v_lshlrev_b32_e32 v74, 16, v88
	v_and_b32_e32 v75, 0xffff0000, v88
	v_pk_fma_f32 v[72:73], v[56:57], v[74:75], v[72:73]
	v_lshlrev_b32_e32 v74, 16, v92
	v_and_b32_e32 v75, 0xffff0000, v92
	v_pk_fma_f32 v[72:73], v[60:61], v[74:75], v[72:73]
	v_lshlrev_b32_e32 v74, 16, v100
	v_and_b32_e32 v75, 0xffff0000, v100
	v_pk_fma_f32 v[72:73], v[64:65], v[74:75], v[72:73]
	v_lshlrev_b32_e32 v74, 16, v77
	v_and_b32_e32 v75, 0xffff0000, v77
	v_pk_fma_f32 v[74:75], v[54:55], v[74:75], v[70:71]
	v_lshlrev_b32_e32 v76, 16, v89
	v_and_b32_e32 v77, 0xffff0000, v89
	v_pk_fma_f32 v[74:75], v[58:59], v[76:77], v[74:75]
	v_lshlrev_b32_e32 v76, 16, v93
	v_and_b32_e32 v77, 0xffff0000, v93
	v_pk_fma_f32 v[74:75], v[62:63], v[76:77], v[74:75]
	v_lshlrev_b32_e32 v76, 16, v101
	v_and_b32_e32 v77, 0xffff0000, v101
	v_pk_fma_f32 v[74:75], v[66:67], v[76:77], v[74:75]
	v_lshlrev_b32_e32 v76, 16, v78
	v_and_b32_e32 v77, 0xffff0000, v78
	v_pk_fma_f32 v[76:77], v[32:33], v[76:77], v[48:49]
	v_lshlrev_b32_e32 v80, 16, v90
	v_and_b32_e32 v81, 0xffff0000, v90
	v_pk_fma_f32 v[76:77], v[36:37], v[80:81], v[76:77]
	v_lshlrev_b32_e32 v80, 16, v94
	v_and_b32_e32 v81, 0xffff0000, v94
	v_pk_fma_f32 v[76:77], v[40:41], v[80:81], v[76:77]
	v_lshlrev_b32_e32 v80, 16, v102
	v_and_b32_e32 v81, 0xffff0000, v102
	v_lshlrev_b32_e32 v78, 16, v79
	v_and_b32_e32 v79, 0xffff0000, v79
	v_pk_fma_f32 v[76:77], v[44:45], v[80:81], v[76:77]
	v_pk_fma_f32 v[78:79], v[34:35], v[78:79], v[50:51]
	v_lshlrev_b32_e32 v80, 16, v91
	v_and_b32_e32 v81, 0xffff0000, v91
	v_pk_fma_f32 v[78:79], v[38:39], v[80:81], v[78:79]
	v_lshlrev_b32_e32 v80, 16, v95
	v_and_b32_e32 v81, 0xffff0000, v95
	v_pk_fma_f32 v[78:79], v[42:43], v[80:81], v[78:79]
	v_lshlrev_b32_e32 v80, 16, v103
	v_and_b32_e32 v81, 0xffff0000, v103
	v_pk_fma_f32 v[78:79], v[46:47], v[80:81], v[78:79]
	v_cvt_pk_bf16_f32 v80, v72, v73
	v_cvt_pk_bf16_f32 v81, v74, v75
	v_cvt_pk_bf16_f32 v82, v76, v77
	v_subrev_u32_e32 v112, 35, v126
	v_cvt_pk_bf16_f32 v83, v78, v79
	ds_write_b128 v85, v[80:83]
	ds_write_b128 v84, v[72:75] offset:34304
	ds_write_b128 v84, v[76:79] offset:34320
	s_waitcnt lgkmcnt(0)
	s_barrier
	v_lshlrev_b64 v[72:73], 11, v[112:113]
	v_lshl_add_u64 v[72:73], v[122:123], 0, v[72:73]
	global_load_dwordx4 v[72:75], v[72:73], off
.LBB0_601:
	v_subrev_u32_e32 v76, 34, v126
	v_mov_b32_e32 v77, v113
	v_lshlrev_b64 v[76:77], 11, v[76:77]
	v_lshl_add_u64 v[76:77], v[122:123], 0, v[76:77]
	global_load_dwordx4 v[80:83], v[76:77], off
.LBB0_603:
	v_subrev_u32_e32 v76, 33, v126
	v_mov_b32_e32 v77, v113
	v_lshlrev_b64 v[76:77], 11, v[76:77]
	v_lshl_add_u64 v[76:77], v[122:123], 0, v[76:77]
	global_load_dwordx4 v[84:87], v[76:77], off
.LBB0_605:
	v_subrev_u32_e32 v78, 32, v126
	v_mov_b32_e32 v79, v113
	v_lshlrev_b64 v[78:79], 11, v[78:79]
	v_lshl_add_u64 v[78:79], v[122:123], 0, v[78:79]
	global_load_dwordx4 v[96:99], v[78:79], off
.LBB0_607:
	v_add_u32_e32 v76, -3, v126
	v_mov_b32_e32 v77, v113
	v_lshlrev_b64 v[76:77], 11, v[76:77]
	v_lshl_add_u64 v[76:77], v[122:123], 0, v[76:77]
	global_load_dwordx4 v[76:79], v[76:77], off
; #define LAS __attribute__((address_space(3)))
; template <bool PASSB>
; __device__ __forceinline__ void lru_unit(LAS unsigned char* lds, const Params& p, int b, int hd, int chunk) {
;     ...
;         for (int tb = 0; tb < 4; ++tb) {
;             f32x4 ar = (f32x4){0.f, 0.f, 0.f, 0.f}, ai = (f32x4){0.f, 0.f, 0.f, 0.f};
; #pragma unroll
;             for (int ks = 0; ks < 4; ++ks) {
;                 const bf16x8 a = *(const LAS bf16x8*)(XCB + (tb * 16 + fr) * 272 + (ks * 32 + fq * 8) * 2);
;                 ar = __builtin_amdgcn_mfma_f32_16x16x32_bf16(a, wf[0][ks], ar, 0, 0, 0);
;                 ai = __builtin_amdgcn_mfma_f32_16x16x32_bf16(a, wf[1][ks], ai, 0, 0, 0);
;             }
; #pragma unroll
;             for (int j = 0; j < 4; ++j) {
;                 const int token = fq * 16 + tb * 4 + j;
;                 const float xcv = XCF[token * 132 + chl];
;                 const float e1 = __expf(fminf(-(ar[j] + brv), 40.f)), e2 = __expf(fminf(-(ai[j] + biv), 40.f));
;                 const float inv = __builtin_amdgcn_rcpf((1.0f + e1) * (1.0f + e2));
;                 const float r = inv * (1.0f + e2), ig = inv * (1.0f + e1);
;                 const float a = __expf(clv * r);
;                 const float bb = __builtin_amdgcn_sqrtf(fmaxf(1.0f - a * a, 0.f)) * (ig * xcv);
;                 hrun = a * hrun + bb; prun *= a;
;                 if (PASSB) { hl[tb * 4 + j] = hrun; pl[tb * 4 + j] = prun; }
;             }
;         }
.LBB0_609:
	v_add_u32_e32 v88, -2, v126
	v_mov_b32_e32 v89, v113
	v_lshlrev_b64 v[88:89], 11, v[88:89]
	v_lshl_add_u64 v[88:89], v[122:123], 0, v[88:89]
	global_load_dwordx4 v[88:91], v[88:89], off
.LBB0_611:
	v_add_u32_e32 v92, -1, v126
	v_mov_b32_e32 v93, v113
	v_lshlrev_b64 v[92:93], 11, v[92:93]
	v_lshl_add_u64 v[92:93], v[122:123], 0, v[92:93]
	global_load_dwordx4 v[92:95], v[92:93], off
.LBB0_613:
	v_mov_b32_e32 v127, v113
	v_lshlrev_b64 v[100:101], 11, v[126:127]
	v_lshl_add_u64 v[100:101], v[122:123], 0, v[100:101]
	global_load_dwordx4 v[100:103], v[100:101], off
.LBB0_615:
	v_add3_u32 v145, s12, v116, v130
	ds_read_b128 v[104:107], v145
	ds_read_b128 v[108:111], v145 offset:64
	ds_read_b128 v[146:149], v145 offset:128
	ds_read_b128 v[150:153], v145 offset:192
	v_lshlrev_b32_e32 v112, 2, v114
	s_waitcnt lgkmcnt(3)
	v_mfma_f32_16x16x32_bf16 v[140:143], v[104:107], v[24:27], 0
	v_mfma_f32_16x16x32_bf16 v[104:107], v[104:107], v[28:31], 0
	s_waitcnt lgkmcnt(2)
	v_mfma_f32_16x16x32_bf16 v[140:143], v[108:111], v[16:19], v[140:143]
	v_mfma_f32_16x16x32_bf16 v[104:107], v[108:111], v[20:23], v[104:107]
	s_waitcnt lgkmcnt(1)
	v_mfma_f32_16x16x32_bf16 v[108:111], v[146:149], v[8:11], v[140:143]
	v_mfma_f32_16x16x32_bf16 v[104:107], v[146:149], v[12:15], v[104:107]
	s_nop 3
	v_add3_u32 v143, s12, v112, v121
	v_add_u32_e32 v127, 0x4400, v143
	s_waitcnt lgkmcnt(0)
	v_mfma_f32_16x16x32_bf16 v[108:111], v[150:153], v[0:3], v[108:111]
	v_mfma_f32_16x16x32_bf16 v[104:107], v[150:153], v[4:7], v[104:107]
	s_nop 6
	v_fma_f32 v108, v108, s72, v200
	v_fma_f32 v104, v104, s72, v201
	v_min_f32_e32 v108, s73, v108
	v_min_f32_e32 v104, s73, v104
	v_exp_f32_e32 v108, v108
	v_exp_f32_e32 v104, v104
	v_fma_f32 v105, v105, s72, v201
	v_min_f32_e32 v105, s73, v105
	v_add_f32_e32 v108, 1.0, v108
	v_add_f32_e32 v129, 1.0, v104
	v_mul_f32_e32 v104, v108, v129
	v_rcp_f32_e32 v140, v104
	v_fma_f32 v109, v109, s72, v200
	v_exp_f32_e32 v128, v105
	ds_read2_b32 v[104:105], v127 offset1:132
	v_mul_f32_e32 v127, v129, v140
	v_min_f32_e32 v109, s73, v109
	v_mul_f32_e32 v127, v202, v127
	v_exp_f32_e32 v109, v109
	v_exp_f32_e32 v127, v127
	v_add_f32_e32 v128, 1.0, v128
	v_mul_f32_e32 v108, v108, v140
	v_add_f32_e32 v109, 1.0, v109
	v_fma_f32 v140, -v127, v127, 1.0 clamp
	v_fma_f32 v110, v110, s72, v200
	v_fma_f32 v106, v106, s72, v201
	v_mul_f32_e32 v129, v109, v128
	v_min_f32_e32 v110, s73, v110
	v_min_f32_e32 v106, s73, v106
	v_rcp_f32_e32 v129, v129
	v_sqrt_f32_e32 v140, v140
	v_exp_f32_e32 v110, v110
	v_exp_f32_e32 v106, v106
	s_waitcnt lgkmcnt(0)
	v_mul_f32_e32 v104, v104, v108
	v_mul_f32_e32 v108, v128, v129
	v_mul_f32_e32 v140, v104, v140
	v_mul_f32_e32 v104, v109, v129
	v_mul_f32_e32 v108, v202, v108
	v_mul_f32_e32 v104, v105, v104
	v_add_f32_e32 v105, 1.0, v110
	v_add_f32_e32 v106, 1.0, v106
	v_mul_f32_e32 v110, v105, v106
	v_exp_f32_e32 v108, v108
	v_rcp_f32_e32 v110, v110
	v_fmac_f32_e32 v140, 0, v127
	v_fma_f32 v109, -v108, v108, 1.0 clamp
	v_mul_f32_e32 v106, v106, v110
	v_mul_f32_e32 v106, v202, v106
	v_sqrt_f32_e32 v109, v109
	v_exp_f32_e32 v158, v106
	v_mul_f32_e32 v141, v108, v140
	v_fmac_f32_e32 v141, v104, v109
	v_add_u32_e32 v104, 0x4800, v143
	ds_read2_b32 v[128:129], v104 offset0:8 offset1:140
	ds_read_b128 v[146:149], v145 offset:4352
	v_fma_f32 v104, -v158, v158, 1.0 clamp
	v_sqrt_f32_e32 v159, v104
	v_fma_f32 v104, v111, s72, v200
	v_min_f32_e32 v104, s73, v104
	v_mul_f32_e32 v142, v127, v108
	v_mul_f32_e32 v144, v105, v110
	ds_read_b128 v[108:111], v145 offset:4416
	v_exp_f32_e32 v154, v104
	v_fma_f32 v104, v107, s72, v201
	v_min_f32_e32 v155, s73, v104
	s_waitcnt lgkmcnt(1)
	v_mfma_f32_16x16x32_bf16 v[150:153], v[146:149], v[24:27], 0
	v_add_f32_e32 v160, 1.0, v154
	v_mul_f32_e32 v128, v128, v144
	v_mul_f32_e32 v144, v158, v141
	v_mfma_f32_16x16x32_bf16 v[104:107], v[146:149], v[28:31], 0
	v_exp_f32_e32 v155, v155
	ds_read_b128 v[146:149], v145 offset:4480
	s_waitcnt lgkmcnt(1)
	v_mfma_f32_16x16x32_bf16 v[150:153], v[108:111], v[16:19], v[150:153]
	v_fmac_f32_e32 v144, v128, v159
	v_add_f32_e32 v161, 1.0, v155
	ds_read_b128 v[154:157], v145 offset:4544
	v_mfma_f32_16x16x32_bf16 v[104:107], v[108:111], v[20:23], v[104:107]
	v_mul_f32_e32 v108, v160, v161
	v_rcp_f32_e32 v162, v108
	s_waitcnt lgkmcnt(1)
	v_mfma_f32_16x16x32_bf16 v[108:111], v[146:149], v[8:11], v[150:153]
	v_mul_f32_e32 v128, v161, v162
	v_mul_f32_e32 v128, v202, v128
	v_mfma_f32_16x16x32_bf16 v[104:107], v[146:149], v[12:15], v[104:107]
	v_exp_f32_e32 v128, v128
	v_mul_f32_e32 v147, v160, v162
	s_waitcnt lgkmcnt(0)
	v_mfma_f32_16x16x32_bf16 v[108:111], v[154:157], v[0:3], v[108:111]
	v_mul_f32_e32 v146, v158, v142
	v_fma_f32 v148, -v128, v128, 1.0 clamp
	v_mfma_f32_16x16x32_bf16 v[104:107], v[154:157], v[4:7], v[104:107]
	v_sqrt_f32_e32 v148, v148
	s_nop 2
	s_nop 0
	v_fma_f32 v108, v108, s72, v200
	v_min_f32_e32 v108, s73, v108
	v_exp_f32_e32 v108, v108
	v_fma_f32 v104, v104, s72, v201
	v_min_f32_e32 v104, s73, v104
	v_exp_f32_e32 v104, v104
	v_add_f32_e32 v108, 1.0, v108
	v_fma_f32 v109, v109, s72, v200
	v_fma_f32 v105, v105, s72, v201
	v_add_f32_e32 v104, 1.0, v104
	v_mul_f32_e32 v149, v108, v104
	v_rcp_f32_e32 v149, v149
	v_min_f32_e32 v109, s73, v109
	v_min_f32_e32 v105, s73, v105
	v_mul_f32_e32 v104, v104, v149
	v_mul_f32_e32 v104, v202, v104
	v_exp_f32_e32 v104, v104
	v_exp_f32_e32 v109, v109
	v_exp_f32_e32 v105, v105
	v_mul_f32_e32 v129, v129, v147
	v_mul_f32_e32 v147, v128, v144
	v_fmac_f32_e32 v147, v129, v148
	v_mul_f32_e32 v148, v128, v146
	v_add_u32_e32 v128, 0x4c00, v143
	ds_read2_b32 v[128:129], v128 offset0:16 offset1:148
	v_fma_f32 v150, -v104, v104, 1.0 clamp
	v_add_f32_e32 v109, 1.0, v109
	v_add_f32_e32 v105, 1.0, v105
	v_sqrt_f32_e32 v150, v150
	v_mul_f32_e32 v151, v109, v105
	v_rcp_f32_e32 v151, v151
	v_mul_f32_e32 v108, v108, v149
	s_waitcnt lgkmcnt(0)
; #define LAS __attribute__((address_space(3)))
; template <bool PASSB>
; __device__ __forceinline__ void lru_unit(LAS unsigned char* lds, const Params& p, int b, int hd, int chunk) {
;     ...
;         for (int tb = 0; tb < 4; ++tb) {
;             f32x4 ar = (f32x4){0.f, 0.f, 0.f, 0.f}, ai = (f32x4){0.f, 0.f, 0.f, 0.f};
; #pragma unroll
;             for (int ks = 0; ks < 4; ++ks) {
;                 const bf16x8 a = *(const LAS bf16x8*)(XCB + (tb * 16 + fr) * 272 + (ks * 32 + fq * 8) * 2);
;                 ar = __builtin_amdgcn_mfma_f32_16x16x32_bf16(a, wf[0][ks], ar, 0, 0, 0);
;                 ai = __builtin_amdgcn_mfma_f32_16x16x32_bf16(a, wf[1][ks], ai, 0, 0, 0);
;             }
; #pragma unroll
;             for (int j = 0; j < 4; ++j) {
;                 const int token = fq * 16 + tb * 4 + j;
;                 const float xcv = XCF[token * 132 + chl];
;                 const float e1 = __expf(fminf(-(ar[j] + brv), 40.f)), e2 = __expf(fminf(-(ai[j] + biv), 40.f));
;                 const float inv = __builtin_amdgcn_rcpf((1.0f + e1) * (1.0f + e2));
;                 const float r = inv * (1.0f + e2), ig = inv * (1.0f + e1);
;                 const float a = __expf(clv * r);
;                 const float bb = __builtin_amdgcn_sqrtf(fmaxf(1.0f - a * a, 0.f)) * (ig * xcv);
;                 hrun = a * hrun + bb; prun *= a;
;                 if (PASSB) { hl[tb * 4 + j] = hrun; pl[tb * 4 + j] = prun; }
;             }
;         }
	v_mul_f32_e32 v108, v128, v108
	v_mul_f32_e32 v149, v108, v150
	v_fmac_f32_e32 v149, v147, v104
	v_mul_f32_e32 v150, v148, v104
	v_mul_f32_e32 v104, v109, v151
	v_fma_f32 v109, v110, s72, v200
	v_fma_f32 v106, v106, s72, v201
	v_min_f32_e32 v109, s73, v109
	v_min_f32_e32 v106, s73, v106
	v_exp_f32_e32 v109, v109
	v_exp_f32_e32 v106, v106
	v_mul_f32_e32 v105, v105, v151
	v_mul_f32_e32 v105, v202, v105
	v_add_f32_e32 v109, 1.0, v109
	v_add_f32_e32 v106, 1.0, v106
	v_mul_f32_e32 v110, v109, v106
	v_exp_f32_e32 v105, v105
	v_rcp_f32_e32 v110, v110
	v_mul_f32_e32 v104, v129, v104
	v_fma_f32 v108, -v105, v105, 1.0 clamp
	v_mul_f32_e32 v151, v105, v149
	v_mul_f32_e32 v152, v105, v150
	v_mul_f32_e32 v105, v106, v110
	v_mul_f32_e32 v105, v202, v105
	v_sqrt_f32_e32 v108, v108
	v_exp_f32_e32 v153, v105
	v_mul_f32_e32 v162, v109, v110
	v_fmac_f32_e32 v151, v104, v108
	v_add_u32_e32 v104, 0x5000, v143
	ds_read2_b32 v[128:129], v104 offset0:24 offset1:156
	ds_read_b128 v[154:157], v145 offset:8704
	v_fma_f32 v104, -v153, v153, 1.0 clamp
	v_sqrt_f32_e32 v166, v104
	v_fma_f32 v104, v111, s72, v200
	v_min_f32_e32 v104, s73, v104
	ds_read_b128 v[108:111], v145 offset:8768
	v_exp_f32_e32 v163, v104
	v_fma_f32 v104, v107, s72, v201
	v_min_f32_e32 v164, s73, v104
	s_waitcnt lgkmcnt(1)
	v_mfma_f32_16x16x32_bf16 v[158:161], v[154:157], v[24:27], 0
	v_mul_f32_e32 v167, v128, v162
	v_add_f32_e32 v168, 1.0, v163
	v_mul_f32_e32 v128, v153, v151
	v_mfma_f32_16x16x32_bf16 v[104:107], v[154:157], v[28:31], 0
	v_exp_f32_e32 v164, v164
	ds_read_b128 v[154:157], v145 offset:8832
	s_waitcnt lgkmcnt(1)
	v_mfma_f32_16x16x32_bf16 v[158:161], v[108:111], v[16:19], v[158:161]
	v_fmac_f32_e32 v128, v167, v166
	v_add_f32_e32 v169, 1.0, v164
	ds_read_b128 v[162:165], v145 offset:8896
	v_mfma_f32_16x16x32_bf16 v[104:107], v[108:111], v[20:23], v[104:107]
	v_mul_f32_e32 v108, v168, v169
	v_rcp_f32_e32 v171, v108
	v_mul_f32_e32 v153, v153, v152
	s_waitcnt lgkmcnt(1)
	v_mfma_f32_16x16x32_bf16 v[108:111], v[154:157], v[8:11], v[158:161]
	v_mfma_f32_16x16x32_bf16 v[104:107], v[154:157], v[12:15], v[104:107]
	s_nop 1
	v_mul_f32_e32 v158, v169, v171
	v_mul_f32_e32 v154, v202, v158
	s_waitcnt lgkmcnt(0)
	v_mfma_f32_16x16x32_bf16 v[108:111], v[162:165], v[0:3], v[108:111]
	v_exp_f32_e32 v154, v154
	v_mul_f32_e32 v155, v168, v171
	v_mul_f32_e32 v155, v129, v155
	v_mfma_f32_16x16x32_bf16 v[104:107], v[162:165], v[4:7], v[104:107]
	v_fma_f32 v156, -v154, v154, 1.0 clamp
	s_nop 2
	v_fma_f32 v108, v108, s72, v200
	v_min_f32_e32 v108, s73, v108
	v_exp_f32_e32 v108, v108
	s_nop 0
	v_fma_f32 v104, v104, s72, v201
	v_min_f32_e32 v104, s73, v104
	v_exp_f32_e32 v104, v104
	v_add_f32_e32 v108, 1.0, v108
	v_fma_f32 v109, v109, s72, v200
	v_fma_f32 v105, v105, s72, v201
	v_add_f32_e32 v104, 1.0, v104
	v_mul_f32_e32 v157, v108, v104
	v_rcp_f32_e32 v158, v157
	v_min_f32_e32 v109, s73, v109
	v_min_f32_e32 v105, s73, v105
	v_mul_f32_e32 v104, v104, v158
	v_exp_f32_e32 v109, v109
	v_exp_f32_e32 v105, v105
	v_sqrt_f32_e32 v156, v156
	v_mul_f32_e32 v104, v202, v104
	v_exp_f32_e32 v104, v104
	v_mul_f32_e32 v129, v154, v128
	v_add_f32_e32 v159, 1.0, v109
	v_add_f32_e32 v105, 1.0, v105
	v_fmac_f32_e32 v129, v155, v156
	v_add_u32_e32 v155, 0x5400, v143
	v_mul_f32_e32 v109, v159, v105
	ds_read2_b32 v[156:157], v155 offset0:32 offset1:164
	v_rcp_f32_e32 v160, v109
	v_fma_f32 v155, -v104, v104, 1.0 clamp
	v_fma_f32 v110, v110, s72, v200
	v_fma_f32 v106, v106, s72, v201
	v_sqrt_f32_e32 v155, v155
	v_min_f32_e32 v110, s73, v110
	v_min_f32_e32 v106, s73, v106
	v_mul_f32_e32 v108, v108, v158
	v_mul_f32_e32 v105, v105, v160
	s_waitcnt lgkmcnt(0)
	v_mul_f32_e32 v108, v156, v108
	v_mul_f32_e32 v105, v202, v105
	v_exp_f32_e32 v156, v110
	v_exp_f32_e32 v106, v106
	v_mul_f32_e32 v154, v154, v153
	v_mul_f32_e32 v109, v108, v155
	v_exp_f32_e32 v105, v105
	v_fmac_f32_e32 v109, v129, v104
	v_mul_f32_e32 v155, v154, v104
	v_mul_f32_e32 v104, v159, v160
	v_mul_f32_e32 v104, v157, v104
	v_add_f32_e32 v157, 1.0, v156
	v_add_f32_e32 v106, 1.0, v106
	v_mul_f32_e32 v156, v157, v106
	v_fma_f32 v108, -v105, v105, 1.0 clamp
	v_rcp_f32_e32 v162, v156
	v_sqrt_f32_e32 v108, v108
	v_mul_f32_e32 v110, v105, v109
	v_mul_f32_e32 v156, v105, v155
	v_mul_f32_e32 v105, v106, v162
	v_mul_f32_e32 v105, v202, v105
	v_fmac_f32_e32 v110, v104, v108
	v_add_u32_e32 v104, 0x5800, v143
	v_exp_f32_e32 v106, v105
	ds_read2_b32 v[104:105], v104 offset0:40 offset1:172
	ds_read_b128 v[158:161], v145 offset:13056
	v_mul_f32_e32 v108, v157, v162
	ds_read_b128 v[162:165], v145 offset:13120
	ds_read_b128 v[172:175], v145 offset:13184
	s_waitcnt lgkmcnt(2)
	v_mfma_f32_16x16x32_bf16 v[166:169], v[158:161], v[24:27], 0
	v_fma_f32 v111, v111, s72, v200
	v_fma_f32 v107, v107, s72, v201
	v_min_f32_e32 v111, s73, v111
	v_mfma_f32_16x16x32_bf16 v[158:161], v[158:161], v[28:31], 0
	v_min_f32_e32 v107, s73, v107
	s_waitcnt lgkmcnt(1)
	v_mfma_f32_16x16x32_bf16 v[166:169], v[162:165], v[16:19], v[166:169]
	v_exp_f32_e32 v111, v111
	v_exp_f32_e32 v107, v107
	v_fma_f32 v157, -v106, v106, 1.0 clamp
	v_mfma_f32_16x16x32_bf16 v[158:161], v[162:165], v[20:23], v[158:161]
	ds_read_b128 v[162:165], v145 offset:13248
	v_mul_f32_e32 v104, v104, v108
	v_add_f32_e32 v108, 1.0, v111
	s_waitcnt lgkmcnt(1)
	v_mfma_f32_16x16x32_bf16 v[166:169], v[172:175], v[8:11], v[166:169]
	v_add_f32_e32 v107, 1.0, v107
	v_mul_f32_e32 v111, v108, v107
	v_mfma_f32_16x16x32_bf16 v[158:161], v[172:175], v[12:15], v[158:161]
	v_sqrt_f32_e32 v157, v157
	v_rcp_f32_e32 v171, v111
	v_mul_f32_e32 v111, v106, v110
	s_waitcnt lgkmcnt(0)
; template <bool PASSB>
; __device__ __forceinline__ void lru_unit(LAS unsigned char* lds, const Params& p, int b, int hd, int chunk) {
;     ...
;         if (PASSB) {
; #pragma unroll
;             for (int q = 0; q < 16; ++q) gvv[q] = GA[obase + (size_t)q * 1024];
;         }
;     ...
;             for (int j = 0; j < 4; ++j) {
;                 const int token = fq * 16 + tb * 4 + j;
;                 const float xcv = XCF[token * 132 + chl];
;                 const float e1 = __expf(fminf(-(ar[j] + brv), 40.f)), e2 = __expf(fminf(-(ai[j] + biv), 40.f));
;                 const float inv = __builtin_amdgcn_rcpf((1.0f + e1) * (1.0f + e2));
;                 const float r = inv * (1.0f + e2), ig = inv * (1.0f + e1);
;                 const float a = __expf(clv * r);
;                 const float bb = __builtin_amdgcn_sqrtf(fmaxf(1.0f - a * a, 0.f)) * (ig * xcv);
;                 hrun = a * hrun + bb; prun *= a;
;                 if (PASSB) { hl[tb * 4 + j] = hrun; pl[tb * 4 + j] = prun; }
;             }
;         }
;         const float P0 = __shfl(prun, fr), H0 = __shfl(hrun, fr), P1 = __shfl(prun, fr + 16), H1 = __shfl(hrun, fr + 16);
;         const float P2 = __shfl(prun, fr + 32), H2 = __shfl(hrun, fr + 32), P3 = __shfl(prun, fr + 48), H3 = __shfl(hrun, fr + 48);
;         const float s0 = P0 * Cst + H0, s1 = P1 * s0 + H1, s2 = P2 * s1 + H2, s3 = P3 * s2 + H3;
;         const float cin = fq == 0 ? Cst : (fq == 1 ? s0 : (fq == 2 ? s1 : s2));
;         Cst = s3;
	v_mfma_f32_16x16x32_bf16 v[166:169], v[162:165], v[0:3], v[166:169]
	v_fmac_f32_e32 v111, v104, v157
	v_mul_f32_e32 v104, v107, v171
	v_mul_f32_e32 v145, v106, v156
	v_mfma_f32_16x16x32_bf16 v[160:163], v[162:165], v[4:7], v[158:161]
	v_mul_f32_e32 v106, v108, v171
	s_nop 2
	v_fma_f32 v108, v166, s72, v200
	v_mul_f32_e32 v104, v202, v104
	v_min_f32_e32 v108, s73, v108
	s_nop 0
	v_fma_f32 v157, v160, s72, v201
	v_min_f32_e32 v157, s73, v157
	v_exp_f32_e32 v104, v104
	v_exp_f32_e32 v108, v108
	v_exp_f32_e32 v157, v157
	v_mul_f32_e32 v105, v105, v106
	v_fma_f32 v107, -v104, v104, 1.0 clamp
	v_add_f32_e32 v108, 1.0, v108
	v_add_f32_e32 v158, 1.0, v157
	v_mul_f32_e32 v157, v108, v158
	v_sqrt_f32_e32 v107, v107
	v_rcp_f32_e32 v159, v157
	v_mul_f32_e32 v157, v104, v111
	v_fma_f32 v160, v167, s72, v200
	v_fmac_f32_e32 v157, v105, v107
	v_mul_f32_e32 v105, v158, v159
	v_fma_f32 v161, v161, s72, v201
	v_mul_f32_e32 v105, v202, v105
	v_min_f32_e32 v160, s73, v160
	v_min_f32_e32 v161, s73, v161
	v_exp_f32_e32 v106, v105
	v_exp_f32_e32 v160, v160
	v_exp_f32_e32 v161, v161
	v_mul_f32_e32 v158, v104, v145
	v_add_u32_e32 v104, 0x5c00, v143
	ds_read2_b32 v[104:105], v104 offset0:48 offset1:180
	v_fma_f32 v107, -v106, v106, 1.0 clamp
	v_add_f32_e32 v164, 1.0, v160
	v_add_f32_e32 v160, 1.0, v161
	v_mul_f32_e32 v161, v164, v160
	v_sqrt_f32_e32 v107, v107
	v_rcp_f32_e32 v161, v161
	v_mul_f32_e32 v108, v108, v159
	s_waitcnt lgkmcnt(0)
	v_mul_f32_e32 v104, v104, v108
	v_mul_f32_e32 v159, v104, v107
	v_mul_f32_e32 v104, v160, v161
	v_mul_f32_e32 v104, v202, v104
	v_exp_f32_e32 v104, v104
	v_fmac_f32_e32 v159, v157, v106
	v_mul_f32_e32 v160, v158, v106
	v_mul_f32_e32 v106, v164, v161
	v_mul_f32_e32 v105, v105, v106
	v_fma_f32 v106, v168, s72, v200
	v_fma_f32 v108, v162, s72, v201
	v_fma_f32 v107, -v104, v104, 1.0 clamp
	v_min_f32_e32 v106, s73, v106
	v_min_f32_e32 v108, s73, v108
	v_sqrt_f32_e32 v107, v107
	v_exp_f32_e32 v106, v106
	v_exp_f32_e32 v108, v108
	v_mul_f32_e32 v161, v104, v159
	v_mul_f32_e32 v162, v104, v160
	v_add_u32_e32 v104, 0x6000, v143
	v_fma_f32 v143, v169, s72, v200
	v_fma_f32 v163, v163, s72, v201
	v_fmac_f32_e32 v161, v105, v107
	v_add_f32_e32 v106, 1.0, v106
	v_add_f32_e32 v107, 1.0, v108
	v_min_f32_e32 v143, s73, v143
	v_min_f32_e32 v163, s73, v163
	v_mul_f32_e32 v105, v106, v107
	v_rcp_f32_e32 v108, v105
	v_exp_f32_e32 v143, v143
	v_exp_f32_e32 v163, v163
	ds_read2_b32 v[104:105], v104 offset0:56 offset1:188
	v_mul_f32_e32 v107, v107, v108
	v_add_f32_e32 v164, 1.0, v143
	v_add_f32_e32 v143, 1.0, v163
	v_mul_f32_e32 v107, v202, v107
	v_mul_f32_e32 v163, v164, v143
	v_rcp_f32_e32 v165, v163
	v_exp_f32_e32 v107, v107
	v_mul_f32_e32 v106, v106, v108
	s_waitcnt lgkmcnt(0)
	v_mul_f32_e32 v104, v104, v106
	v_mul_f32_e32 v106, v143, v165
	v_fma_f32 v108, -v107, v107, 1.0 clamp
	v_mul_f32_e32 v106, v202, v106
	v_sqrt_f32_e32 v108, v108
	v_exp_f32_e32 v106, v106
	v_mul_f32_e32 v143, v107, v161
	v_mul_f32_e32 v163, v107, v162
	v_fmac_f32_e32 v143, v104, v108
	v_fma_f32 v104, -v106, v106, 1.0 clamp
	v_sqrt_f32_e32 v104, v104
	v_mul_f32_e32 v107, v164, v165
	v_mul_f32_e32 v105, v105, v107
	v_mul_f32_e32 v164, v106, v143
	v_fmac_f32_e32 v164, v105, v104
	v_lshl_add_u64 v[104:105], v[124:125], 0, s[8:9]
	v_add_co_u32_e32 v166, vcc, 0xa000000, v104
	v_mul_f32_e32 v165, v106, v163
	s_nop 0
	v_addc_co_u32_e32 v167, vcc, 0, v105, vcc
	v_add_co_u32_e32 v168, vcc, 0xa001000, v104
	ds_bpermute_b32 v185, v117, v165
	s_nop 0
	v_addc_co_u32_e32 v169, vcc, 0, v105, vcc
	v_add_co_u32_e32 v172, vcc, 0xa002000, v104
	ds_bpermute_b32 v176, v117, v164
	s_nop 0
	v_addc_co_u32_e32 v173, vcc, 0, v105, vcc
	v_add_co_u32_e32 v190, vcc, 0xa003000, v104
	ds_bpermute_b32 v187, v117, v165 offset:64
	s_nop 0
	v_addc_co_u32_e32 v191, vcc, 0, v105, vcc
	global_load_ushort v189, v[166:167], off
	global_load_ushort v186, v[166:167], off offset:2048
	global_load_ushort v184, v[168:169], off
	global_load_ushort v181, v[168:169], off offset:2048
	global_load_ushort v179, v[172:173], off
	s_nop 0
	global_load_ushort v173, v[172:173], off offset:2048
	s_nop 0
	global_load_ushort v177, v[190:191], off
	global_load_ushort v171, v[190:191], off offset:2048
	v_add_co_u32_e32 v166, vcc, 0xa004000, v104
	ds_bpermute_b32 v182, v117, v164 offset:64
	s_nop 0
	v_addc_co_u32_e32 v167, vcc, 0, v105, vcc
	v_add_co_u32_e32 v168, vcc, 0xa005000, v104
	ds_bpermute_b32 v188, v117, v165 offset:128
	s_nop 0
	v_addc_co_u32_e32 v169, vcc, 0, v105, vcc
	v_add_co_u32_e32 v190, vcc, 0xa006000, v104
	ds_bpermute_b32 v174, v117, v164 offset:128
	s_nop 0
	v_addc_co_u32_e32 v191, vcc, 0, v105, vcc
	v_add_co_u32_e32 v192, vcc, 0xa007000, v104
	ds_bpermute_b32 v175, v117, v165 offset:192
	s_nop 0
	v_addc_co_u32_e32 v193, vcc, 0, v105, vcc
	global_load_ushort v183, v[166:167], off
	global_load_ushort v180, v[166:167], off offset:2048
	global_load_ushort v178, v[168:169], off
	global_load_ushort v172, v[168:169], off offset:2048
	s_nop 0
	global_load_ushort v169, v[190:191], off
	global_load_ushort v167, v[190:191], off offset:2048
	global_load_ushort v168, v[192:193], off
	global_load_ushort v166, v[192:193], off offset:2048
	ds_bpermute_b32 v106, v117, v164 offset:192
	s_waitcnt lgkmcnt(6)
	v_fmac_f32_e32 v176, v137, v185
	s_waitcnt lgkmcnt(4)
	v_fmac_f32_e32 v182, v176, v187
	v_or_b32_e32 v108, 64, v117
	v_or_b32_e32 v107, 0x80, v117
	s_waitcnt lgkmcnt(2)
	v_fmac_f32_e32 v174, v182, v188
	v_cmp_lt_i32_e32 vcc, 0, v135
	s_and_saveexec_b64 s[10:11], vcc
	s_cbranch_execz .LBB0_621
	v_cmp_ne_u32_e32 vcc, 1, v135
	s_and_saveexec_b64 s[12:13], vcc
	s_xor_b64 s[12:13], exec, s[12:13]
	v_cndmask_b32_e64 v137, v174, v182, s[0:1]
	s_andn2_saveexec_b64 s[12:13], s[12:13]
	v_mov_b32_e32 v137, v176
	s_or_b64 exec, exec, s[12:13]
